# also: rwkv r/k/v epilogue dwordx4 stores; K=1024 loops no longer issue the 3 duplicate tail K-tile DMAs
# speedup vs baseline: 1.0182x; 1.0067x over previous
.LBB0_829:
	s_cmp_lt_u32 s19, 29
	s_cbranch_scc1 .Lnd0_w8
	s_waitcnt vmcnt(0)
	s_branch .Lnd0_wd

.Lnd0_wd:
	s_waitcnt lgkmcnt(0)
	s_barrier
	s_add_i32 s19, s19, 1
	s_add_i32 s13, s13, 32
	s_add_i32 s18, s18, 0x8000
	s_cmpk_eq_i32 s13, 0x460
	s_cbranch_scc1 .LBB0_832
.LBB0_830:
	s_and_b32 s34, s18, 0x18000
	s_add_i32 s34, s34, 0
	s_add_i32 s35, s34, s5
	v_add3_u32 v1, s35, v176, v173
	s_add_i32 s34, s34, s4
	s_waitcnt lgkmcnt(0)
	ds_read_b128 v[130:133], v1 offset:16384
	ds_read_b128 v[134:137], v1 offset:17408
	ds_read_b128 v[138:141], v1 offset:18432
	ds_read_b128 v[142:145], v1 offset:19456
	v_add_u32_e32 v1, s34, v176
	s_add_i32 s34, s18, 0x18000
	s_and_b32 s44, s34, 0x18000
	s_cmp_lt_u32 s19, 29
	s_cselect_b32 s38, s13, 0x3e0
	s_lshl_b64 s[34:35], s[38:39], 1
	s_add_i32 s44, s12, s44
	v_add_u32_e32 v1, v1, v173
	ds_read_b128 v[154:157], v1
	ds_read_b128 v[150:153], v1 offset:1024
	ds_read_b128 v[146:149], v1 offset:2048
	s_andn2_b64 vcc, exec, s[0:1]
	s_cmp_lt_u32 s19, 29
	s_cbranch_scc0 .Lnd0_skip
	s_mov_b32 m0, s44
	v_lshl_add_u64 v[194:195], v[160:161], 0, s[34:35]
	global_load_lds_dwordx4 v[194:195], off
	s_add_i32 m0, s44, 0x2000
	v_lshl_add_u64 v[194:195], v[162:163], 0, s[34:35]
	global_load_lds_dwordx4 v[194:195], off
	s_add_i32 m0, s44, 0x4000
	v_lshl_add_u64 v[194:195], v[164:165], 0, s[34:35]
	global_load_lds_dwordx4 v[194:195], off
	s_add_i32 m0, s44, 0x6000
	v_lshl_add_u64 v[194:195], v[166:167], 0, s[34:35]
	global_load_lds_dwordx4 v[194:195], off
.Lnd0_skip:
	s_cbranch_vccnz .LBB0_829
	s_waitcnt lgkmcnt(0)
	v_mfma_f32_16x16x32_bf16 v[126:129], v[130:133], v[154:157], v[126:129]
	ds_read_b128 v[178:181], v1 offset:3072
	v_mfma_f32_16x16x32_bf16 v[122:125], v[134:137], v[154:157], v[122:125]
	v_mfma_f32_16x16x32_bf16 v[118:121], v[138:141], v[154:157], v[118:121]
	v_mfma_f32_16x16x32_bf16 v[114:117], v[142:145], v[154:157], v[114:117]
	v_mfma_f32_16x16x32_bf16 v[110:113], v[130:133], v[150:153], v[110:113]
	ds_read_b128 v[154:157], v1 offset:4096
	v_mfma_f32_16x16x32_bf16 v[106:109], v[134:137], v[150:153], v[106:109]
	v_mfma_f32_16x16x32_bf16 v[102:105], v[138:141], v[150:153], v[102:105]
	v_mfma_f32_16x16x32_bf16 v[98:101], v[142:145], v[150:153], v[98:101]
	v_mfma_f32_16x16x32_bf16 v[94:97], v[130:133], v[146:149], v[94:97]
	ds_read_b128 v[150:153], v1 offset:5120
	v_mfma_f32_16x16x32_bf16 v[90:93], v[134:137], v[146:149], v[90:93]
	v_mfma_f32_16x16x32_bf16 v[86:89], v[138:141], v[146:149], v[86:89]
	v_mfma_f32_16x16x32_bf16 v[82:85], v[142:145], v[146:149], v[82:85]
	s_waitcnt lgkmcnt(0)
	v_mfma_f32_16x16x32_bf16 v[78:81], v[130:133], v[178:181], v[78:81]
	ds_read_b128 v[146:149], v1 offset:6144
	v_mfma_f32_16x16x32_bf16 v[74:77], v[134:137], v[178:181], v[74:77]
	v_mfma_f32_16x16x32_bf16 v[70:73], v[138:141], v[178:181], v[70:73]
	v_mfma_f32_16x16x32_bf16 v[66:69], v[142:145], v[178:181], v[66:69]
	v_mfma_f32_16x16x32_bf16 v[62:65], v[130:133], v[154:157], v[62:65]
	ds_read_b128 v[178:181], v1 offset:7168
	v_mfma_f32_16x16x32_bf16 v[58:61], v[134:137], v[154:157], v[58:61]
	v_mfma_f32_16x16x32_bf16 v[54:57], v[138:141], v[154:157], v[54:57]
	v_mfma_f32_16x16x32_bf16 v[50:53], v[142:145], v[154:157], v[50:53]
	v_mfma_f32_16x16x32_bf16 v[46:49], v[130:133], v[150:153], v[46:49]
	v_mfma_f32_16x16x32_bf16 v[42:45], v[134:137], v[150:153], v[42:45]
	v_mfma_f32_16x16x32_bf16 v[38:41], v[138:141], v[150:153], v[38:41]
	v_mfma_f32_16x16x32_bf16 v[34:37], v[142:145], v[150:153], v[34:37]
	s_waitcnt lgkmcnt(0)
	v_mfma_f32_16x16x32_bf16 v[30:33], v[130:133], v[146:149], v[30:33]
	v_mfma_f32_16x16x32_bf16 v[26:29], v[134:137], v[146:149], v[26:29]
	v_mfma_f32_16x16x32_bf16 v[22:25], v[138:141], v[146:149], v[22:25]
	v_mfma_f32_16x16x32_bf16 v[14:17], v[142:145], v[146:149], v[14:17]
	v_mfma_f32_16x16x32_bf16 v[18:21], v[130:133], v[178:181], v[18:21]
	v_mfma_f32_16x16x32_bf16 v[10:13], v[134:137], v[178:181], v[10:13]
	v_mfma_f32_16x16x32_bf16 v[6:9], v[138:141], v[178:181], v[6:9]
	v_mfma_f32_16x16x32_bf16 v[2:5], v[142:145], v[178:181], v[2:5]
	s_branch .LBB0_829
.LBB0_832:
	s_waitcnt vmcnt(0)
	s_waitcnt lgkmcnt(0)
	v_lshlrev_b32_e32 v130, 2, v171
	s_waitcnt lgkmcnt(0)
	s_barrier
	v_lshl_or_b32 v1, s11, 7, v172
	v_lshl_or_b32 v130, s10, 6, v130
	s_add_u32 s0, s96, s8
	s_addc_u32 s1, s97, s9
	v_add_u32_e32 v206, s6, v1
	v_or_b32_e32 v130, s7, v130
	v_lshlrev_b32_e32 v130, 1, v130
	v_and_b32_e32 v207, 1, v171
	v_mul_u32_u24_e32 v207, 24, v207
	v_add_u32_e32 v130, v130, v207
	v_mov_b32_e32 v131, v0
	v_ashrrev_i32_e32 v207, 31, v206
	v_mov_b32_e32 v204, v206
	v_mov_b32_e32 v205, v207
	v_lshlrev_b64 v[204:205], 11, v[204:205]
	v_lshl_add_u64 v[204:205], s[0:1], 0, v[204:205]
	v_lshl_add_u64 v[204:205], v[204:205], 0, v[130:131]
	v_mov_b32_e32 v208, 0x8000
	v_mov_b32_e32 v209, v0
	v_cvt_pk_bf16_f32 v196, v126, v127
	v_cvt_pk_bf16_f32 v197, v128, v129
	v_cvt_pk_bf16_f32 v198, v122, v123
	v_cvt_pk_bf16_f32 v199, v124, v125
	v_cvt_pk_bf16_f32 v200, v118, v119
	v_cvt_pk_bf16_f32 v201, v120, v121
	v_cvt_pk_bf16_f32 v202, v114, v115
	v_cvt_pk_bf16_f32 v203, v116, v117
	v_cmp_gt_i32_e32 vcc, s45, v206
	s_nop 0
	v_permlane16_swap_b32_e32 v196, v198
	v_permlane16_swap_b32_e32 v197, v199
	v_permlane16_swap_b32_e32 v200, v202
	v_permlane16_swap_b32_e32 v201, v203
	s_and_saveexec_b64 s[4:5], vcc
	global_store_dwordx4 v[204:205], v[196:199], off
	global_store_dwordx4 v[204:205], v[200:203], off offset:64
	s_or_b64 exec, exec, s[4:5]
	v_lshl_add_u64 v[204:205], v[204:205], 0, v[208:209]
	v_add_u32_e32 v206, 16, v206
	v_cvt_pk_bf16_f32 v196, v110, v111
	v_cvt_pk_bf16_f32 v197, v112, v113
	v_cvt_pk_bf16_f32 v198, v106, v107
	v_cvt_pk_bf16_f32 v199, v108, v109
	v_cvt_pk_bf16_f32 v200, v102, v103
	v_cvt_pk_bf16_f32 v201, v104, v105
	v_cvt_pk_bf16_f32 v202, v98, v99
	v_cvt_pk_bf16_f32 v203, v100, v101
	v_cmp_gt_i32_e32 vcc, s45, v206
	s_nop 0
	v_permlane16_swap_b32_e32 v196, v198
	v_permlane16_swap_b32_e32 v197, v199
	v_permlane16_swap_b32_e32 v200, v202
	v_permlane16_swap_b32_e32 v201, v203
	s_and_saveexec_b64 s[4:5], vcc
	global_store_dwordx4 v[204:205], v[196:199], off
	global_store_dwordx4 v[204:205], v[200:203], off offset:64
	s_or_b64 exec, exec, s[4:5]
	v_lshl_add_u64 v[204:205], v[204:205], 0, v[208:209]
	v_add_u32_e32 v206, 16, v206
	v_cvt_pk_bf16_f32 v196, v94, v95
	v_cvt_pk_bf16_f32 v197, v96, v97
	v_cvt_pk_bf16_f32 v198, v90, v91
	v_cvt_pk_bf16_f32 v199, v92, v93
	v_cvt_pk_bf16_f32 v200, v86, v87
	v_cvt_pk_bf16_f32 v201, v88, v89
	v_cvt_pk_bf16_f32 v202, v82, v83
	v_cvt_pk_bf16_f32 v203, v84, v85
	v_cmp_gt_i32_e32 vcc, s45, v206
	s_nop 0
	v_permlane16_swap_b32_e32 v196, v198
	v_permlane16_swap_b32_e32 v197, v199
	v_permlane16_swap_b32_e32 v200, v202
	v_permlane16_swap_b32_e32 v201, v203
	s_and_saveexec_b64 s[4:5], vcc
	global_store_dwordx4 v[204:205], v[196:199], off
	global_store_dwordx4 v[204:205], v[200:203], off offset:64
	s_or_b64 exec, exec, s[4:5]
	v_lshl_add_u64 v[204:205], v[204:205], 0, v[208:209]
	v_add_u32_e32 v206, 16, v206
	v_cvt_pk_bf16_f32 v196, v78, v79
	v_cvt_pk_bf16_f32 v197, v80, v81
	v_cvt_pk_bf16_f32 v198, v74, v75
	v_cvt_pk_bf16_f32 v199, v76, v77
	v_cvt_pk_bf16_f32 v200, v70, v71
	v_cvt_pk_bf16_f32 v201, v72, v73
	v_cvt_pk_bf16_f32 v202, v66, v67
	v_cvt_pk_bf16_f32 v203, v68, v69
	v_cmp_gt_i32_e32 vcc, s45, v206
	s_nop 0
	v_permlane16_swap_b32_e32 v196, v198
	v_permlane16_swap_b32_e32 v197, v199
	v_permlane16_swap_b32_e32 v200, v202
	v_permlane16_swap_b32_e32 v201, v203
	s_and_saveexec_b64 s[4:5], vcc
	global_store_dwordx4 v[204:205], v[196:199], off
	global_store_dwordx4 v[204:205], v[200:203], off offset:64
	s_or_b64 exec, exec, s[4:5]
	v_lshl_add_u64 v[204:205], v[204:205], 0, v[208:209]
	v_add_u32_e32 v206, 16, v206
	v_cvt_pk_bf16_f32 v196, v62, v63
	v_cvt_pk_bf16_f32 v197, v64, v65
	v_cvt_pk_bf16_f32 v198, v58, v59
	v_cvt_pk_bf16_f32 v199, v60, v61
	v_cvt_pk_bf16_f32 v200, v54, v55
	v_cvt_pk_bf16_f32 v201, v56, v57
	v_cvt_pk_bf16_f32 v202, v50, v51
	v_cvt_pk_bf16_f32 v203, v52, v53
	v_cmp_gt_i32_e32 vcc, s45, v206
	s_nop 0
	v_permlane16_swap_b32_e32 v196, v198
	v_permlane16_swap_b32_e32 v197, v199
	v_permlane16_swap_b32_e32 v200, v202
	v_permlane16_swap_b32_e32 v201, v203
	s_and_saveexec_b64 s[4:5], vcc
	global_store_dwordx4 v[204:205], v[196:199], off
	global_store_dwordx4 v[204:205], v[200:203], off offset:64
	s_or_b64 exec, exec, s[4:5]
	v_lshl_add_u64 v[204:205], v[204:205], 0, v[208:209]
	v_add_u32_e32 v206, 16, v206
	v_cvt_pk_bf16_f32 v196, v46, v47
	v_cvt_pk_bf16_f32 v197, v48, v49
	v_cvt_pk_bf16_f32 v198, v42, v43
	v_cvt_pk_bf16_f32 v199, v44, v45
	v_cvt_pk_bf16_f32 v200, v38, v39
	v_cvt_pk_bf16_f32 v201, v40, v41
	v_cvt_pk_bf16_f32 v202, v34, v35
	v_cvt_pk_bf16_f32 v203, v36, v37
	v_cmp_gt_i32_e32 vcc, s45, v206
	s_nop 0
	v_permlane16_swap_b32_e32 v196, v198
	v_permlane16_swap_b32_e32 v197, v199
	v_permlane16_swap_b32_e32 v200, v202
	v_permlane16_swap_b32_e32 v201, v203
	s_and_saveexec_b64 s[4:5], vcc
	global_store_dwordx4 v[204:205], v[196:199], off
	global_store_dwordx4 v[204:205], v[200:203], off offset:64
	s_or_b64 exec, exec, s[4:5]
	v_lshl_add_u64 v[204:205], v[204:205], 0, v[208:209]
	v_add_u32_e32 v206, 16, v206
	v_cvt_pk_bf16_f32 v196, v30, v31
	v_cvt_pk_bf16_f32 v197, v32, v33
	v_cvt_pk_bf16_f32 v198, v26, v27
	v_cvt_pk_bf16_f32 v199, v28, v29
	v_cvt_pk_bf16_f32 v200, v22, v23
	v_cvt_pk_bf16_f32 v201, v24, v25
	v_cvt_pk_bf16_f32 v202, v14, v15
	v_cvt_pk_bf16_f32 v203, v16, v17
	v_cmp_gt_i32_e32 vcc, s45, v206
	s_nop 0
	v_permlane16_swap_b32_e32 v196, v198
	v_permlane16_swap_b32_e32 v197, v199
	v_permlane16_swap_b32_e32 v200, v202
	v_permlane16_swap_b32_e32 v201, v203
	s_and_saveexec_b64 s[4:5], vcc
	global_store_dwordx4 v[204:205], v[196:199], off
	global_store_dwordx4 v[204:205], v[200:203], off offset:64
	s_or_b64 exec, exec, s[4:5]
	v_lshl_add_u64 v[204:205], v[204:205], 0, v[208:209]
	v_add_u32_e32 v206, 16, v206
	v_cvt_pk_bf16_f32 v196, v18, v19
	v_cvt_pk_bf16_f32 v197, v20, v21
	v_cvt_pk_bf16_f32 v198, v10, v11
	v_cvt_pk_bf16_f32 v199, v12, v13
	v_cvt_pk_bf16_f32 v200, v6, v7
	v_cvt_pk_bf16_f32 v201, v8, v9
	v_cvt_pk_bf16_f32 v202, v2, v3
	v_cvt_pk_bf16_f32 v203, v4, v5
	v_cmp_gt_i32_e32 vcc, s45, v206
	s_nop 0
	v_permlane16_swap_b32_e32 v196, v198
	v_permlane16_swap_b32_e32 v197, v199
	v_permlane16_swap_b32_e32 v200, v202
	v_permlane16_swap_b32_e32 v201, v203
	s_and_saveexec_b64 s[4:5], vcc
	global_store_dwordx4 v[204:205], v[196:199], off
	global_store_dwordx4 v[204:205], v[200:203], off offset:64
	s_or_b64 exec, exec, s[4:5]
	s_mov_b64 s[4:5], exec
	s_branch .LBB0_433

.LBB0_1581:
	s_cmp_lt_u32 s24, 29
	s_cbranch_scc1 .Lnd1_w8
	s_waitcnt vmcnt(0)
	s_branch .Lnd1_wd

.Lnd1_wd:
	s_waitcnt lgkmcnt(0)
	s_barrier
	s_add_i32 s24, s24, 1
	s_add_i32 s23, s23, 32
	s_add_i32 s22, s22, 0x8000
	s_cmpk_eq_i32 s23, 0x460
	s_cbranch_scc1 .LBB0_1584
.LBB0_1582:
	s_and_b32 s6, s22, 0x18000
	s_add_i32 s6, s6, 0
	s_add_i32 s25, s6, s20
	v_add3_u32 v0, s25, v173, v172
	s_add_i32 s6, s6, s19
	s_waitcnt lgkmcnt(0)
	ds_read_b128 v[130:133], v0 offset:16384
	ds_read_b128 v[134:137], v0 offset:17408
	ds_read_b128 v[138:141], v0 offset:18432
	ds_read_b128 v[142:145], v0 offset:19456
	v_add_u32_e32 v0, s6, v173
	s_add_i32 s6, s22, 0x18000
	s_and_b32 s25, s6, 0x18000
	s_cmp_lt_u32 s24, 29
	s_cselect_b32 s6, s23, 0x3e0
	s_lshl_b64 s[26:27], s[6:7], 1
	s_add_i32 s6, s21, s25
	v_add_u32_e32 v0, v0, v172
	ds_read_b128 v[154:157], v0
	ds_read_b128 v[150:153], v0 offset:1024
	ds_read_b128 v[146:149], v0 offset:2048
	s_and_b64 vcc, exec, s[0:1]
	s_cmp_lt_u32 s24, 29
	s_cbranch_scc0 .Lnd1_skip
	s_mov_b32 m0, s6
	v_lshl_add_u64 v[194:195], v[162:163], 0, s[26:27]
	global_load_lds_dwordx4 v[194:195], off
	s_add_i32 m0, s6, 0x2000
	v_lshl_add_u64 v[194:195], v[164:165], 0, s[26:27]
	global_load_lds_dwordx4 v[194:195], off
	s_add_i32 m0, s6, 0x4000
	v_lshl_add_u64 v[194:195], v[166:167], 0, s[26:27]
	global_load_lds_dwordx4 v[194:195], off
	s_add_i32 m0, s6, 0x6000
	v_lshl_add_u64 v[194:195], v[168:169], 0, s[26:27]
	global_load_lds_dwordx4 v[194:195], off
.Lnd1_skip:
	s_cbranch_vccnz .LBB0_1581
	s_waitcnt lgkmcnt(0)
	v_mfma_f32_16x16x32_bf16 v[126:129], v[130:133], v[154:157], v[126:129]
	ds_read_b128 v[176:179], v0 offset:3072
	v_mfma_f32_16x16x32_bf16 v[122:125], v[134:137], v[154:157], v[122:125]
	v_mfma_f32_16x16x32_bf16 v[118:121], v[138:141], v[154:157], v[118:121]
	v_mfma_f32_16x16x32_bf16 v[114:117], v[142:145], v[154:157], v[114:117]
	v_mfma_f32_16x16x32_bf16 v[110:113], v[130:133], v[150:153], v[110:113]
	ds_read_b128 v[154:157], v0 offset:4096
	v_mfma_f32_16x16x32_bf16 v[106:109], v[134:137], v[150:153], v[106:109]
	v_mfma_f32_16x16x32_bf16 v[102:105], v[138:141], v[150:153], v[102:105]
	v_mfma_f32_16x16x32_bf16 v[98:101], v[142:145], v[150:153], v[98:101]
	v_mfma_f32_16x16x32_bf16 v[94:97], v[130:133], v[146:149], v[94:97]
	ds_read_b128 v[150:153], v0 offset:5120
	v_mfma_f32_16x16x32_bf16 v[90:93], v[134:137], v[146:149], v[90:93]
	v_mfma_f32_16x16x32_bf16 v[86:89], v[138:141], v[146:149], v[86:89]
	v_mfma_f32_16x16x32_bf16 v[82:85], v[142:145], v[146:149], v[82:85]
	s_waitcnt lgkmcnt(0)
	v_mfma_f32_16x16x32_bf16 v[78:81], v[130:133], v[176:179], v[78:81]
	ds_read_b128 v[146:149], v0 offset:6144
	v_mfma_f32_16x16x32_bf16 v[74:77], v[134:137], v[176:179], v[74:77]
	v_mfma_f32_16x16x32_bf16 v[70:73], v[138:141], v[176:179], v[70:73]
	v_mfma_f32_16x16x32_bf16 v[66:69], v[142:145], v[176:179], v[66:69]
	v_mfma_f32_16x16x32_bf16 v[62:65], v[130:133], v[154:157], v[62:65]
	ds_read_b128 v[176:179], v0 offset:7168
	v_mfma_f32_16x16x32_bf16 v[58:61], v[134:137], v[154:157], v[58:61]
	v_mfma_f32_16x16x32_bf16 v[54:57], v[138:141], v[154:157], v[54:57]
	v_mfma_f32_16x16x32_bf16 v[50:53], v[142:145], v[154:157], v[50:53]
	v_mfma_f32_16x16x32_bf16 v[46:49], v[130:133], v[150:153], v[46:49]
	v_mfma_f32_16x16x32_bf16 v[42:45], v[134:137], v[150:153], v[42:45]
	v_mfma_f32_16x16x32_bf16 v[38:41], v[138:141], v[150:153], v[38:41]
	v_mfma_f32_16x16x32_bf16 v[34:37], v[142:145], v[150:153], v[34:37]
	s_waitcnt lgkmcnt(0)
	v_mfma_f32_16x16x32_bf16 v[30:33], v[130:133], v[146:149], v[30:33]
	v_mfma_f32_16x16x32_bf16 v[26:29], v[134:137], v[146:149], v[26:29]
	v_mfma_f32_16x16x32_bf16 v[22:25], v[138:141], v[146:149], v[22:25]
	v_mfma_f32_16x16x32_bf16 v[14:17], v[142:145], v[146:149], v[14:17]
	v_mfma_f32_16x16x32_bf16 v[18:21], v[130:133], v[176:179], v[18:21]
	v_mfma_f32_16x16x32_bf16 v[10:13], v[134:137], v[176:179], v[10:13]
	v_mfma_f32_16x16x32_bf16 v[6:9], v[138:141], v[176:179], v[6:9]
	v_mfma_f32_16x16x32_bf16 v[2:5], v[142:145], v[176:179], v[2:5]
	s_branch .LBB0_1581

.LBB0_1914:
	s_cmp_lt_u32 s12, 29
	s_cbranch_scc1 .Lnd2_w8
	s_waitcnt vmcnt(0)
	s_branch .Lnd2_wd

.Lnd2_wd:
	s_waitcnt lgkmcnt(0)
	s_barrier
	s_add_i32 s12, s12, 1
	s_add_i32 s11, s11, 32
	s_add_i32 s10, s10, 0x8000
	s_cmpk_eq_i32 s11, 0x460
	s_cbranch_scc1 .LBB0_1917
.LBB0_1915:
	s_and_b32 s13, s10, 0x18000
	s_add_i32 s13, s13, 0
	s_add_i32 s14, s13, s8
	v_add3_u32 v0, s14, v178, v177
	s_add_i32 s13, s13, s7
	s_waitcnt lgkmcnt(0)
	ds_read_b128 v[130:133], v0 offset:16384
	ds_read_b128 v[134:137], v0 offset:17408
	ds_read_b128 v[138:141], v0 offset:18432
	ds_read_b128 v[142:145], v0 offset:19456
	v_add_u32_e32 v0, s13, v178
	s_add_i32 s13, s10, 0x18000
	s_and_b32 s13, s13, 0x18000
	s_cmp_lt_u32 s12, 29
	s_cselect_b32 s18, s11, 0x3e0
	s_lshl_b64 s[14:15], s[18:19], 1
	s_add_i32 s13, s9, s13
	v_add_u32_e32 v0, v0, v177
	ds_read_b128 v[154:157], v0
	ds_read_b128 v[150:153], v0 offset:1024
	ds_read_b128 v[146:149], v0 offset:2048
	s_andn2_b64 vcc, exec, s[0:1]
	s_cmp_lt_u32 s12, 29
	s_cbranch_scc0 .Lnd2_skip
	s_mov_b32 m0, s13
	v_lshl_add_u64 v[194:195], v[162:163], 0, s[14:15]
	global_load_lds_dwordx4 v[194:195], off
	s_add_i32 m0, s13, 0x2000
	v_lshl_add_u64 v[194:195], v[164:165], 0, s[14:15]
	global_load_lds_dwordx4 v[194:195], off
	s_add_i32 m0, s13, 0x4000
	v_lshl_add_u64 v[194:195], v[166:167], 0, s[14:15]
	global_load_lds_dwordx4 v[194:195], off
	s_add_i32 m0, s13, 0x6000
	v_lshl_add_u64 v[194:195], v[168:169], 0, s[14:15]
	global_load_lds_dwordx4 v[194:195], off
.Lnd2_skip:
	s_cbranch_vccnz .LBB0_1914
	s_waitcnt lgkmcnt(0)
	v_mfma_f32_16x16x32_bf16 v[126:129], v[130:133], v[154:157], v[126:129]
	ds_read_b128 v[180:183], v0 offset:3072
	v_mfma_f32_16x16x32_bf16 v[122:125], v[134:137], v[154:157], v[122:125]
	v_mfma_f32_16x16x32_bf16 v[118:121], v[138:141], v[154:157], v[118:121]
	v_mfma_f32_16x16x32_bf16 v[114:117], v[142:145], v[154:157], v[114:117]
	v_mfma_f32_16x16x32_bf16 v[110:113], v[130:133], v[150:153], v[110:113]
	ds_read_b128 v[154:157], v0 offset:4096
	v_mfma_f32_16x16x32_bf16 v[106:109], v[134:137], v[150:153], v[106:109]
	v_mfma_f32_16x16x32_bf16 v[102:105], v[138:141], v[150:153], v[102:105]
	v_mfma_f32_16x16x32_bf16 v[98:101], v[142:145], v[150:153], v[98:101]
	v_mfma_f32_16x16x32_bf16 v[94:97], v[130:133], v[146:149], v[94:97]
	ds_read_b128 v[150:153], v0 offset:5120
	v_mfma_f32_16x16x32_bf16 v[90:93], v[134:137], v[146:149], v[90:93]
	v_mfma_f32_16x16x32_bf16 v[86:89], v[138:141], v[146:149], v[86:89]
	v_mfma_f32_16x16x32_bf16 v[82:85], v[142:145], v[146:149], v[82:85]
	s_waitcnt lgkmcnt(0)
	v_mfma_f32_16x16x32_bf16 v[78:81], v[130:133], v[180:183], v[78:81]
	ds_read_b128 v[146:149], v0 offset:6144
	v_mfma_f32_16x16x32_bf16 v[74:77], v[134:137], v[180:183], v[74:77]
	v_mfma_f32_16x16x32_bf16 v[70:73], v[138:141], v[180:183], v[70:73]
	v_mfma_f32_16x16x32_bf16 v[66:69], v[142:145], v[180:183], v[66:69]
	v_mfma_f32_16x16x32_bf16 v[62:65], v[130:133], v[154:157], v[62:65]
	ds_read_b128 v[180:183], v0 offset:7168
	v_mfma_f32_16x16x32_bf16 v[58:61], v[134:137], v[154:157], v[58:61]
	v_mfma_f32_16x16x32_bf16 v[54:57], v[138:141], v[154:157], v[54:57]
	v_mfma_f32_16x16x32_bf16 v[50:53], v[142:145], v[154:157], v[50:53]
	v_mfma_f32_16x16x32_bf16 v[46:49], v[130:133], v[150:153], v[46:49]
	v_mfma_f32_16x16x32_bf16 v[42:45], v[134:137], v[150:153], v[42:45]
	v_mfma_f32_16x16x32_bf16 v[38:41], v[138:141], v[150:153], v[38:41]
	v_mfma_f32_16x16x32_bf16 v[34:37], v[142:145], v[150:153], v[34:37]
	s_waitcnt lgkmcnt(0)
	v_mfma_f32_16x16x32_bf16 v[30:33], v[130:133], v[146:149], v[30:33]
	v_mfma_f32_16x16x32_bf16 v[26:29], v[134:137], v[146:149], v[26:29]
	v_mfma_f32_16x16x32_bf16 v[22:25], v[138:141], v[146:149], v[22:25]
	v_mfma_f32_16x16x32_bf16 v[18:21], v[142:145], v[146:149], v[18:21]
	v_mfma_f32_16x16x32_bf16 v[14:17], v[130:133], v[180:183], v[14:17]
	v_mfma_f32_16x16x32_bf16 v[10:13], v[134:137], v[180:183], v[10:13]
	v_mfma_f32_16x16x32_bf16 v[6:9], v[138:141], v[180:183], v[6:9]
	v_mfma_f32_16x16x32_bf16 v[2:5], v[142:145], v[180:183], v[2:5]
	s_branch .LBB0_1914

.LBB0_3006:
	s_cmp_lt_u32 s22, 29
	s_cbranch_scc1 .Lnd3_w8
	s_waitcnt vmcnt(0)
	s_branch .Lnd3_wd

.Lnd3_wd:
	s_waitcnt lgkmcnt(0)
	s_barrier
	s_add_i32 s22, s22, 1
	s_add_i32 s21, s21, 32
	s_add_i32 s20, s20, 0x8000
	s_cmpk_eq_i32 s21, 0x460
	s_cbranch_scc1 .LBB0_3009
.LBB0_3007:
	s_and_b32 s4, s20, 0x18000
	s_add_i32 s4, s4, 0
	s_add_i32 s23, s4, s18
	v_add3_u32 v0, s23, v173, v172
	s_add_i32 s4, s4, s17
	s_waitcnt lgkmcnt(0)
	ds_read_b128 v[130:133], v0 offset:16384
	ds_read_b128 v[134:137], v0 offset:17408
	ds_read_b128 v[138:141], v0 offset:18432
	ds_read_b128 v[142:145], v0 offset:19456
	v_add_u32_e32 v0, s4, v173
	s_add_i32 s4, s20, 0x18000
	s_and_b32 s23, s4, 0x18000
	s_cmp_lt_u32 s22, 29
	s_cselect_b32 s4, s21, 0x3e0
	s_lshl_b64 s[24:25], s[4:5], 1
	s_add_i32 s4, s19, s23
	v_add_u32_e32 v0, v0, v172
	ds_read_b128 v[154:157], v0
	ds_read_b128 v[150:153], v0 offset:1024
	ds_read_b128 v[146:149], v0 offset:2048
	s_and_b64 vcc, exec, s[0:1]
	s_cmp_lt_u32 s22, 29
	s_cbranch_scc0 .Lnd3_skip
	s_mov_b32 m0, s4
	v_lshl_add_u64 v[194:195], v[162:163], 0, s[24:25]
	global_load_lds_dwordx4 v[194:195], off
	s_add_i32 m0, s4, 0x2000
	v_lshl_add_u64 v[194:195], v[164:165], 0, s[24:25]
	global_load_lds_dwordx4 v[194:195], off
	s_add_i32 m0, s4, 0x4000
	v_lshl_add_u64 v[194:195], v[166:167], 0, s[24:25]
	global_load_lds_dwordx4 v[194:195], off
	s_add_i32 m0, s4, 0x6000
	v_lshl_add_u64 v[194:195], v[168:169], 0, s[24:25]
	global_load_lds_dwordx4 v[194:195], off
